# v21 + 128-row gate unit variant: dwordx4 output stores via permlane32_swap, single wait for the u loads
# speedup vs baseline: 1.0013x; 1.0013x over previous
; #define GASP __attribute__((address_space(1)))
; __device__ __forceinline__ void gate_unit(const Params& p, LAS unsigned char* L, int row0, int n, int g, int sample_b) {
;     ...
;         bf16_t* op = (bf16_t*)(ws + O_MIX) + (size_t)(row0 + te) * D + 512 + g * 128 + dh * 64 + 4 * hi;
; #pragma unroll
;         for (int db = 0; db < 2; ++db)
; #pragma unroll
;             for (int g4 = 0; g4 < 4; ++g4) { const u32x2 u2 = uu[db * 4 + g4];
;                 const float u0 = __uint_as_float(u2.x << 16), u1 = __uint_as_float(u2.x & 0xffff0000u), u2f = __uint_as_float(u2.y << 16), u3 = __uint_as_float(u2.y & 0xffff0000u);
;                 u32x2 w; w.x = pk2(u0 * (OT[db][4 * g4] + bias), u1 * (OT[db][4 * g4 + 1] + bias)); w.y = pk2(u2f * (OT[db][4 * g4 + 2] + bias), u3 * (OT[db][4 * g4 + 3] + bias));
;                 *(GASP u32x2*)(op + db * 32 + 8 * g4) = w; }
.LBB0_921:
	v_lshlrev_b32_e32 v34, 11, v106
	v_mov_b32_e32 v35, v1
	v_lshl_add_u64 v[34:35], s[22:23], 0, v[34:35]
	v_lshlrev_b32_e32 v36, 2, v83
	v_lshl_add_u64 v[34:35], v[0:1], 1, v[34:35]
	s_waitcnt vmcnt(0)
	v_lshlrev_b32_e32 v38, 16, v98
	v_and_b32_e32 v39, 0xffff0000, v98
	s_nop 1
	v_pk_add_f32 v[18:19], v[82:83], v[18:19] op_sel_hi:[0,1]
	v_lshl_add_u64 v[34:35], s[84:85], 1, v[34:35]
	v_lshlrev_b32_e32 v0, 1, v36
	v_pk_mul_f32 v[18:19], v[18:19], v[38:39]
	v_lshlrev_b32_e32 v38, 16, v99
	v_and_b32_e32 v39, 0xffff0000, v99
	v_pk_add_f32 v[20:21], v[82:83], v[20:21] op_sel_hi:[0,1]
	v_lshl_add_u64 v[34:35], v[34:35], 0, v[0:1]
	v_pk_mul_f32 v[20:21], v[20:21], v[38:39]
	v_cvt_pk_bf16_f32 v210, v18, v19
	v_cvt_pk_bf16_f32 v211, v20, v21
	v_add_co_u32_e32 v20, vcc, s89, v34
	s_mov_b64 s[6:7], 0x2a9a1400
	s_nop 0
	v_addc_co_u32_e32 v21, vcc, 0, v35, vcc
	v_lshlrev_b32_e32 v18, 16, v96
	v_and_b32_e32 v19, 0xffff0000, v96
	v_pk_add_f32 v[20:21], v[82:83], v[22:23] op_sel_hi:[0,1]
	v_pk_mul_f32 v[18:19], v[20:21], v[18:19]
	v_lshlrev_b32_e32 v20, 16, v97
	v_and_b32_e32 v21, 0xffff0000, v97
	v_pk_add_f32 v[22:23], v[82:83], v[24:25] op_sel_hi:[0,1]
	v_pk_mul_f32 v[20:21], v[22:23], v[20:21]
	v_lshl_add_u64 v[36:37], v[34:35], 0, s[6:7]
	v_mbcnt_lo_u32_b32 v218, -1, 0
	v_mbcnt_hi_u32_b32 v218, -1, v218
	v_and_b32_e32 v218, 32, v218
	v_lshrrev_b32_e32 v218, 2, v218
	v_mov_b32_e32 v219, 0
	v_lshl_add_u64 v[220:221], v[36:37], 0, v[218:219]
	v_cvt_pk_bf16_f32 v212, v18, v19
	v_cvt_pk_bf16_f32 v213, v20, v21
	s_nop 1
	v_permlane32_swap_b32_e32 v210, v212
	v_permlane32_swap_b32_e32 v211, v213
	global_store_dwordx4 v[220:221], v[210:213], off
	v_lshlrev_b32_e32 v18, 16, v94
	v_and_b32_e32 v19, 0xffff0000, v94
	v_pk_add_f32 v[20:21], v[82:83], v[26:27] op_sel_hi:[0,1]
	v_pk_mul_f32 v[18:19], v[20:21], v[18:19]
	v_lshlrev_b32_e32 v20, 16, v95
	v_and_b32_e32 v21, 0xffff0000, v95
	v_pk_add_f32 v[22:23], v[82:83], v[28:29] op_sel_hi:[0,1]
	v_pk_mul_f32 v[20:21], v[22:23], v[20:21]
	v_cvt_pk_bf16_f32 v214, v18, v19
	v_cvt_pk_bf16_f32 v215, v20, v21
	v_lshlrev_b32_e32 v18, 16, v92
	v_and_b32_e32 v19, 0xffff0000, v92
	v_pk_add_f32 v[20:21], v[82:83], v[30:31] op_sel_hi:[0,1]
	v_pk_mul_f32 v[18:19], v[20:21], v[18:19]
	v_lshlrev_b32_e32 v20, 16, v93
	v_and_b32_e32 v21, 0xffff0000, v93
	v_pk_add_f32 v[22:23], v[82:83], v[32:33] op_sel_hi:[0,1]
	v_pk_mul_f32 v[20:21], v[22:23], v[20:21]
	v_cvt_pk_bf16_f32 v216, v18, v19
	v_cvt_pk_bf16_f32 v217, v20, v21
	s_nop 1
	v_permlane32_swap_b32_e32 v214, v216
	v_permlane32_swap_b32_e32 v215, v217
	global_store_dwordx4 v[220:221], v[214:217], off offset:32
	v_lshlrev_b32_e32 v18, 16, v90
	v_and_b32_e32 v19, 0xffff0000, v90
	v_pk_add_f32 v[2:3], v[82:83], v[2:3] op_sel_hi:[0,1]
	v_pk_mul_f32 v[2:3], v[2:3], v[18:19]
	v_lshlrev_b32_e32 v18, 16, v91
	v_and_b32_e32 v19, 0xffff0000, v91
	v_pk_add_f32 v[4:5], v[82:83], v[4:5] op_sel_hi:[0,1]
	v_pk_mul_f32 v[4:5], v[4:5], v[18:19]
	v_cvt_pk_bf16_f32 v210, v2, v3
	v_cvt_pk_bf16_f32 v211, v4, v5
	v_lshlrev_b32_e32 v2, 16, v88
	v_and_b32_e32 v3, 0xffff0000, v88
	v_pk_add_f32 v[4:5], v[82:83], v[6:7] op_sel_hi:[0,1]
	v_pk_mul_f32 v[2:3], v[4:5], v[2:3]
	v_lshlrev_b32_e32 v4, 16, v89
	v_and_b32_e32 v5, 0xffff0000, v89
	v_pk_add_f32 v[6:7], v[82:83], v[8:9] op_sel_hi:[0,1]
	v_pk_mul_f32 v[4:5], v[6:7], v[4:5]
	v_cvt_pk_bf16_f32 v212, v2, v3
	v_cvt_pk_bf16_f32 v213, v4, v5
	s_nop 1
	v_permlane32_swap_b32_e32 v210, v212
	v_permlane32_swap_b32_e32 v211, v213
	global_store_dwordx4 v[220:221], v[210:213], off offset:64
	v_lshlrev_b32_e32 v2, 16, v86
	v_and_b32_e32 v3, 0xffff0000, v86
	v_pk_add_f32 v[4:5], v[82:83], v[10:11] op_sel_hi:[0,1]
	v_pk_mul_f32 v[2:3], v[4:5], v[2:3]
	v_lshlrev_b32_e32 v4, 16, v87
	v_and_b32_e32 v5, 0xffff0000, v87
	v_pk_add_f32 v[6:7], v[82:83], v[12:13] op_sel_hi:[0,1]
	v_pk_mul_f32 v[4:5], v[6:7], v[4:5]
	v_cvt_pk_bf16_f32 v214, v2, v3
	v_cvt_pk_bf16_f32 v215, v4, v5
	v_lshlrev_b32_e32 v2, 16, v84
	v_and_b32_e32 v3, 0xffff0000, v84
	v_pk_add_f32 v[4:5], v[82:83], v[14:15] op_sel_hi:[0,1]
	v_pk_mul_f32 v[2:3], v[4:5], v[2:3]
	v_lshlrev_b32_e32 v4, 16, v85
	v_and_b32_e32 v5, 0xffff0000, v85
	v_pk_add_f32 v[6:7], v[82:83], v[16:17] op_sel_hi:[0,1]
	v_pk_mul_f32 v[4:5], v[6:7], v[4:5]
	v_cvt_pk_bf16_f32 v216, v2, v3
	v_cvt_pk_bf16_f32 v217, v4, v5
	s_nop 1
	v_permlane32_swap_b32_e32 v214, v216
	v_permlane32_swap_b32_e32 v215, v217
	global_store_dwordx4 v[220:221], v[214:217], off offset:96
	s_barrier
	s_mov_b64 s[6:7], 0
